# scan S3/S6/S7: all MFMA operand fragment reads issued up front into fresh registers (one LDS round trip per step instead of three)
# baseline (speedup 1.0000x reference)
; __device__ __forceinline__ uint2 pack4(f32x4 v) { uint2 u; u.x = cvt_pk_bf16(v[0], v[1]); u.y = cvt_pk_bf16(v[2], v[3]); return u; }
; #define MFMA16(a, b, c) __builtin_amdgcn_mfma_f32_16x16x32_bf16(a, b, c, 0, 0, 0)
; __device__ __forceinline__ void scan_phase(PREF p, char* smem, const int wid_u) {
;     ...
;         const int mat = wave >> 1, mts = wave & 1;
;         const bf16_t* As = (mat & 1) ? Kt : Bt;
;         const bf16_t* Bs = (mat & 2) ? Rt : At;
;         f32x4 acc[2] = {};
; #pragma unroll
;         for (int ks = 0; ks < 2; ++ks) {
;           const bf16x8 a = ldfrag(As, 72, mts * 16, ks * 32, fr, fq);
; #pragma unroll
;           for (int nt = 0; nt < 2; ++nt) acc[nt] = MFMA16(a, ldfrag(Bs, 72, nt * 16, ks * 32, fr, fq), acc[nt]);
;         }
; #pragma unroll
;         for (int nt = 0; nt < 2; ++nt) {
;           const int tcol = nt * 16 + fr;
;           f32x4 v = acc[nt];
; #pragma unroll
;           for (int jj = 0; jj < 4; ++jj) {
;             const int srow = mts * 16 + fq * 4 + jj;
;             const bool keep = (mat & 2) ? (srow <= tcol) : (srow < tcol);
;             v[jj] = keep ? v[jj] : 0.f;
;           }
;           if (mat == 0) {
; #pragma unroll
;             for (int jj = 0; jj < 4; ++jj) Nab[(mts * 16 + fq * 4 + jj) * 32 + tcol] = v[jj];
;           } else {
;             bf16_t* dst = mat == 1 ? NakT : mat == 2 ? NbrT : NkrT;
;             *(uint2*)(dst + tcol * 40 + mts * 16 + fq * 4) = pack4(v);
.LBB0_540:
	ds_read_b128 v[56:59], v129
	ds_read_b128 v[60:63], v171
	ds_read_b128 v[64:67], v171 offset:2304
	ds_read_b128 v[226:229], v129 offset:64
	ds_read_b128 v[68:71], v171 offset:64
	ds_read_b128 v[230:233], v171 offset:2368
	s_mov_b64 s[40:41], -1
	s_and_b64 vcc, exec, s[60:61]
	s_waitcnt lgkmcnt(4)
	v_mfma_f32_16x16x32_bf16 v[60:63], v[56:59], v[60:63], 0
	s_waitcnt lgkmcnt(3)
	v_mfma_f32_16x16x32_bf16 v[56:59], v[56:59], v[64:67], 0
	s_waitcnt lgkmcnt(1)
	v_mfma_f32_16x16x32_bf16 v[60:63], v[226:229], v[68:71], v[60:63]
	s_waitcnt lgkmcnt(0)
	v_mfma_f32_16x16x32_bf16 v[56:59], v[226:229], v[230:233], v[56:59]
	s_nop 5
	v_cndmask_b32_e64 v60, 0, v60, s[22:23]
	v_cndmask_b32_e64 v61, 0, v61, s[24:25]
	v_cndmask_b32_e64 v62, 0, v62, s[26:27]
	v_cndmask_b32_e64 v63, 0, v63, s[28:29]
	s_cbranch_vccz .LBB0_542
	v_cvt_pk_bf16_f32 v64, v60, v61
	v_cvt_pk_bf16_f32 v65, v62, v63
	ds_write_b64 v180, v[64:65]
	s_mov_b64 s[40:41], 0

; __device__ __forceinline__ void scan_phase(PREF p, char* smem, const int wid_u) {
;     ...
;       {
;         const int tt = wave & 1, rt = wave >> 1;
;         const f32x4 zero = {0.f, 0.f, 0.f, 0.f};
;         const bf16x8 tf = ldfrag(TT, 40, tt * 16, 0, fr, fq);
;         const f32x4 zacc = MFMA16(tf, ldfrag(VNb, 40, rt * 16, 0, fr, fq), zero);
;         const f32x4 wacc = MFMA16(tf, ldfrag(AtTb, 40, rt * 16, 0, fr, fq), zero);
;         *(uint2*)(Zb + (rt * 16 + fr) * 40 + tt * 16 + fq * 4) = pack4(zacc);
;         *(uint2*)(Wb + (rt * 16 + fr) * 40 + tt * 16 + fq * 4) = pack4(wacc);
;       }
;       lds_barrier();
;       f32x4 yacc = {0.f, 0.f, 0.f, 0.f};
;       {
;         const float pl0 = PLs[nt0 * 16 + fr], pl1 = PLs[nt1 * 16 + fr];
;         Sa = Sa * pl0; Sb = Sb * pl1;
;         const bf16x8 zf = ldfrag(Zb, 40, mt * 16, 0, fr, fq), vf = ldfrag(VT, 40, mt * 16, 0, fr, fq), wf = ldfrag(Wb, 40, mt * 16, 0, fr, fq);
;         const bf16x8 bb0 = ldfrag(Bb, 40, nt0 * 16, 0, fr, fq), bb1 = ldfrag(Bb, 40, nt1 * 16, 0, fr, fq);
;         const bf16x8 kb0 = ldfrag(Kb, 40, nt0 * 16, 0, fr, fq), kb1 = ldfrag(Kb, 40, nt1 * 16, 0, fr, fq);
;         const bf16x8 nbr = ldfrag(NbrT, 40, hn * 16, 0, fr, fq), nkr = ldfrag(NkrT, 40, hn * 16, 0, fr, fq);
;         Sa = MFMA16(zf, bb0, Sa); Sa = MFMA16(vf, kb0, Sa);
;         Sb = MFMA16(zf, bb1, Sb); Sb = MFMA16(vf, kb1, Sb);
;         yacc = MFMA16(zf, nbr, yacc); yacc = MFMA16(vf, nkr, yacc);
;         const f32x4 zero = {0.f, 0.f, 0.f, 0.f};
;         const f32x4 g0 = MFMA16(wf, bb0, zero), g1 = MFMA16(wf, bb1, zero);
;         f32x4 ry = MFMA16(wf, nbr, zero);
;         *(uint2*)(GT + (nt0 * 16 + fr) * 72 + mt * 16 + fq * 4) = pack4(g0);
;         *(uint2*)(GT + (nt1 * 16 + fr) * 72 + mt * 16 + fq * 4) = pack4(g1);
;         const uint2 rr = *(const uint2*)(Rt + (hn * 16 + fr) * 72 + mt * 16 + fq * 4);
;         ry[0] += bf_lo(rr.x); ry[1] += bf_hi(rr.x); ry[2] += bf_lo(rr.y); ry[3] += bf_hi(rr.y);
;         *(uint2*)(RyT + (hn * 16 + fr) * 72 + mt * 16 + fq * 4) = pack4(ry);
;       }
;       lds_barrier();
;       {
;         const bf16_t* Scur = Sbf + (c & 1) * 64 * 72;
;         bf16_t* Snext = Sbf + ((c + 1) & 1) * 64 * 72;
; #pragma unroll
;         for (int ks = 0; ks < 2; ++ks) {
;           const bf16x8 af = ldfrag(Scur, 72, mt * 16, ks * 32, fr, fq);
.LBB0_587:
	s_setprio 0
	s_waitcnt lgkmcnt(0)
	s_barrier
	ds_read_b128 v[56:59], v145 offset:13312
	ds_read_b128 v[60:63], v147 offset:39936
	ds_read_b128 v[64:67], v148
	s_and_b32 s40, s95, 64
	s_waitcnt lgkmcnt(1)
	v_mfma_f32_16x16x32_bf16 v[60:63], v[56:59], v[60:63], 0
	s_mulk_i32 s40, 0x90
	s_add_i32 s95, s95, 64
	s_andn2_b64 vcc, exec, s[80:81]
	s_waitcnt lgkmcnt(0)
	v_mfma_f32_16x16x32_bf16 v[56:59], v[56:59], v[64:67], 0
	s_nop 2
	v_cvt_pk_bf16_f32 v60, v60, v61
	v_cvt_pk_bf16_f32 v61, v62, v63
	s_nop 2
	v_cvt_pk_bf16_f32 v56, v56, v57
	v_cvt_pk_bf16_f32 v57, v58, v59
	ds_write2st64_b64 v149, v[56:57], v[60:61] offset0:31 offset1:41
	s_waitcnt lgkmcnt(0)
	s_barrier
	ds_read_b128 v[56:59], v147 offset:20992
	ds_read_b32 v78, v150
	ds_read_b128 v[60:63], v153
	ds_read_b128 v[64:67], v154
	ds_read_b32 v234, v151
	ds_read_b128 v[68:71], v152
	ds_read_b128 v[92:95], v147 offset:15872
	ds_read_b128 v[226:229], v155
	ds_read_b128 v[230:233], v156
	ds_read_b128 v[96:99], v145 offset:8192
	ds_read_b128 v[100:103], v145 offset:10752
	ds_read_b64 v[236:237], v161 offset:53760
	s_waitcnt lgkmcnt(10)
	v_pk_mul_f32 v[50:51], v[50:51], v[78:79] op_sel_hi:[1,0]
	v_pk_mul_f32 v[48:49], v[48:49], v[78:79] op_sel_hi:[1,0]
	s_waitcnt lgkmcnt(7)
	v_pk_mul_f32 v[54:55], v[54:55], v[234:235] op_sel_hi:[1,0]
	v_pk_mul_f32 v[52:53], v[52:53], v[234:235] op_sel_hi:[1,0]
	v_mfma_f32_16x16x32_bf16 v[48:51], v[56:59], v[60:63], v[48:51]
	v_add_u32_e32 v78, s40, v162
	s_and_b32 s40, s95, 64
	s_waitcnt lgkmcnt(5)
	v_mfma_f32_16x16x32_bf16 v[60:63], v[92:95], v[60:63], 0
	s_mulk_i32 s40, 0x90
	v_mfma_f32_16x16x32_bf16 v[52:55], v[56:59], v[64:67], v[52:55]
	v_mfma_f32_16x16x32_bf16 v[64:67], v[92:95], v[64:67], 0
	s_nop 4
	v_cvt_pk_bf16_f32 v60, v60, v61
	v_cvt_pk_bf16_f32 v61, v62, v63
	s_waitcnt lgkmcnt(4)
	v_mfma_f32_16x16x32_bf16 v[48:51], v[68:71], v[226:229], v[48:51]
	s_waitcnt lgkmcnt(3)
	v_mfma_f32_16x16x32_bf16 v[52:55], v[68:71], v[230:233], v[52:55]
	ds_write_b64 v158, v[60:61] offset:26112
	v_cvt_pk_bf16_f32 v60, v64, v65
	v_cvt_pk_bf16_f32 v61, v66, v67
	ds_write_b64 v160, v[60:61] offset:26112
	s_waitcnt lgkmcnt(4)
	s_nop 1
	v_mfma_f32_16x16x32_bf16 v[60:63], v[92:95], v[96:99], 0
	v_add_u32_e32 v92, v130, v157
	s_waitcnt lgkmcnt(2)
	v_lshlrev_b32_e32 v66, 16, v236
	v_and_b32_e32 v67, 0xffff0000, v236
	v_lshlrev_b32_e32 v64, 16, v237
	v_and_b32_e32 v65, 0xffff0000, v237
	s_nop 1
	v_pk_add_f32 v[60:61], v[60:61], v[66:67]
	v_pk_add_f32 v[62:63], v[62:63], v[64:65]
	v_cvt_pk_bf16_f32 v60, v60, v61
	v_cvt_pk_bf16_f32 v61, v62, v63
	ds_write_b64 v161, v[60:61] offset:35328
	s_waitcnt lgkmcnt(0)
	s_barrier
	ds_read_b128 v[60:63], v78
	v_mfma_f32_16x16x32_bf16 v[56:59], v[56:59], v[96:99], 0
	v_mfma_f32_16x16x32_bf16 v[56:59], v[68:71], v[100:103], v[56:59]
	ds_read_b128 v[64:67], v92 offset:26112
	ds_read_b128 v[68:71], v78 offset:64
	ds_read_b128 v[92:95], v92 offset:26176
	v_add_u32_e32 v78, v130, v159
	ds_read_b128 v[96:99], v78 offset:26176
	ds_read_b128 v[226:229], v78 offset:26112
	v_add_u32_e32 v100, v130, v128
	ds_read_b128 v[230:233], v100 offset:35328
	ds_read_b128 v[100:103], v100 offset:35392
	s_waitcnt lgkmcnt(6)
	v_mfma_f32_16x16x32_bf16 v[48:51], v[60:63], v[64:67], v[48:51]
	s_waitcnt lgkmcnt(2)
	v_mfma_f32_16x16x32_bf16 v[52:55], v[60:63], v[226:229], v[52:55]
	v_mfma_f32_16x16x32_bf16 v[48:51], v[68:71], v[92:95], v[48:51]
	v_mfma_f32_16x16x32_bf16 v[52:55], v[68:71], v[96:99], v[52:55]
	s_waitcnt lgkmcnt(1)
	v_mfma_f32_16x16x32_bf16 v[56:59], v[60:63], v[230:233], v[56:59]
	s_nop 4
	v_cvt_pk_bf16_f32 v60, v48, s0
	v_add_u32_e32 v61, s40, v168
	ds_write_b16 v61, v60
	v_cvt_pk_bf16_f32 v60, v52, s0
	ds_write_b16 v61, v60 offset:32
	v_cvt_pk_bf16_f32 v60, v49, s0
	ds_write_b16 v61, v60 offset:144
	v_cvt_pk_bf16_f32 v60, v53, s0
	s_waitcnt lgkmcnt(3)
	v_mfma_f32_16x16x32_bf16 v[56:59], v[68:71], v[100:103], v[56:59]
	ds_write_b16 v61, v60 offset:176
	v_cvt_pk_bf16_f32 v60, v50, s0
	ds_write_b16 v61, v60 offset:288
	v_cvt_pk_bf16_f32 v60, v54, s0
	ds_write_b16 v61, v60 offset:320
	v_cvt_pk_bf16_f32 v60, v51, s0
	ds_write_b16 v61, v60 offset:432
	v_cvt_pk_bf16_f32 v60, v55, s0
	ds_write_b16 v61, v60 offset:464
	s_cbranch_vccnz .LBB0_539
	ds_read_b32 v64, v81 offset:3840
	s_andn2_b64 vcc, exec, s[62:63]
	v_mov_b32_e32 v60, 1.0
	s_cbranch_vccnz .LBB0_590
	ds_read_b32 v60, v163
	s_waitcnt lgkmcnt(1)
	v_cndmask_b32_e64 v61, 1.0, v64, s[20:21]
	s_waitcnt lgkmcnt(0)
	v_mul_f32_e32 v60, v61, v60
